# phase-1 weight conversion rewritten by hand with a 4-tile-deep load pipeline (was 1 tile in flight, latency-bound)
# baseline (speedup 1.0000x reference)
.LBB0_116:
	s_or_b64 exec, exec, s[4:5]
	s_mov_b64 s[0:1], s[86:87]
	s_waitcnt lgkmcnt(0)
	s_barrier
	s_load_dwordx4 s[24:27], s[0:1], 0x8
	s_load_dwordx8 s[12:19], s[0:1], 0x20
	s_load_dwordx2 s[28:29], s[0:1], 0x88
	s_load_dwordx2 s[10:11], s[0:1], 0xb8
	s_bitcmp1_b32 s97, 0
	s_cselect_b64 s[30:31], -1, 0
	s_and_b64 vcc, exec, s[30:31]
	s_cbranch_vccnz .LBB0_152
	s_waitcnt lgkmcnt(0)
	v_lshrrev_b32_e32 v0, 3, v204
	v_and_b32_e32 v1, 7, v204
	v_lshlrev_b32_e32 v1, 3, v1
	v_mul_u32_u24_e32 v2, 65, v0
	v_add_lshl_u32 v2, v2, v1, 2
	v_mul_u32_u24_e32 v4, 65, v1
	v_add_lshl_u32 v4, v4, v0, 2
	s_add_u32 s39, s97, 896
	s_mov_b32 s33, s39
	s_add_u32 s35, s33, 0
	s_cmp_lt_u32 s35, 1152
	s_cbranch_scc0 .Lcv_a_p0_m1
	s_mov_b64 s[64:65], s[18:19]
	s_mov_b32 s5, 1024
	s_mov_b32 s6, 0x10000000
	s_mov_b32 s7, 16
	s_movk_i32 s8, 896
	s_add_u32 s66, s10, 0x700000
	s_addc_u32 s67, s11, 0
	s_movk_i32 s9, 1024
	s_mov_b32 s20, 0
	s_mov_b64 s[70:71], s[24:25]
	s_branch .Lcv_a_p0_c
.Lcv_a_p0_m1:
	s_cmp_lt_u32 s35, 2176
	s_cbranch_scc0 .Lcv_a_p0_m2
	s_mov_b64 s[64:65], s[12:13]
	s_mov_b32 s5, 4096
	s_mov_b32 s6, 0x4000000
	s_mov_b32 s7, 64
	s_movk_i32 s8, 1152
	s_add_u32 s66, s10, 0x900000
	s_addc_u32 s67, s11, 0
	s_movk_i32 s9, 1024
	s_mov_b32 s20, 1
	s_add_u32 s70, s26, 0
	s_addc_u32 s71, s27, 0
	s_branch .Lcv_a_p0_c
.Lcv_a_p0_m2:
	s_cmp_lt_u32 s35, 3200
	s_cbranch_scc0 .Lcv_a_p0_m3
	s_mov_b64 s[64:65], s[14:15]
	s_mov_b32 s5, 1024
	s_mov_b32 s6, 0x10000000
	s_mov_b32 s7, 16
	s_movk_i32 s8, 2176
	s_add_u32 s66, s10, 0x1100000
	s_addc_u32 s67, s11, 0
	s_movk_i32 s9, 4096
	s_mov_b32 s20, 0
	s_mov_b64 s[70:71], s[24:25]
	s_branch .Lcv_a_p0_c
.Lcv_a_p0_m3:
	s_mov_b64 s[64:65], s[28:29]
	s_mov_b32 s5, 3104
	s_mov_b32 s6, 0x4ec4ec5
	s_mov_b32 s7, 52
	s_movk_i32 s8, 3200
	s_add_u32 s66, s10, 0x1900000
	s_addc_u32 s67, s11, 0
	s_movk_i32 s9, 1024
	s_mov_b32 s20, 1
	s_add_u32 s70, s24, 4096
	s_addc_u32 s71, s25, 0
.Lcv_a_p0_c:
	s_sub_u32 s0, s35, s8
	s_mul_hi_u32 s1, s0, s6
	s_mul_i32 s2, s1, s7
	s_sub_u32 s2, s0, s2
	s_lshl_b32 s1, s1, 6
	s_lshl_b32 s2, s2, 6
	s_mul_i32 s3, s1, s5
	s_lshl_b32 s3, s3, 2
	s_add_u32 s64, s64, s3
	s_addc_u32 s65, s65, 0
	v_add_u32_e32 v5, s2, v1
	s_sub_u32 s4, s5, 8
	v_min_u32_e32 v5, s4, v5
	v_mad_u32_u24 v5, v0, s5, v5
	v_lshlrev_b32_e32 v5, 2, v5
	global_load_dwordx4 v[40:43], v5, s[64:65]
	global_load_dwordx4 v[44:47], v5, s[64:65] offset:16
	s_lshl_b32 s3, s1, 2
	s_add_u32 s70, s70, s3
	s_addc_u32 s71, s71, 0
	v_lshlrev_b32_e32 v6, 2, v0
	global_load_dword v48, v6, s[70:71]
	s_mul_i32 s3, s2, s9
	s_add_u32 s3, s3, s1
	s_lshl_b32 s3, s3, 1
	s_add_u32 s40, s66, s3
	s_addc_u32 s41, s67, 0
	s_mov_b32 s42, s9
	s_sub_u32 s43, s5, s2
	s_mov_b32 s44, s20
	s_add_u32 s35, s33, 256
	s_cmp_lt_u32 s35, 1152
	s_cbranch_scc0 .Lcv_a_p1_m1
	s_mov_b64 s[64:65], s[18:19]
	s_mov_b32 s5, 1024
	s_mov_b32 s6, 0x10000000
	s_mov_b32 s7, 16
	s_movk_i32 s8, 896
	s_add_u32 s66, s10, 0x700000
	s_addc_u32 s67, s11, 0
	s_movk_i32 s9, 1024
	s_mov_b32 s20, 0
	s_mov_b64 s[70:71], s[24:25]
	s_branch .Lcv_a_p1_c

.Lcv_a_p1_c:
	s_sub_u32 s0, s35, s8
	s_mul_hi_u32 s1, s0, s6
	s_mul_i32 s2, s1, s7
	s_sub_u32 s2, s0, s2
	s_lshl_b32 s1, s1, 6
	s_lshl_b32 s2, s2, 6
	s_mul_i32 s3, s1, s5
	s_lshl_b32 s3, s3, 2
	s_add_u32 s64, s64, s3
	s_addc_u32 s65, s65, 0
	v_add_u32_e32 v5, s2, v1
	s_sub_u32 s4, s5, 8
	v_min_u32_e32 v5, s4, v5
	v_mad_u32_u24 v5, v0, s5, v5
	v_lshlrev_b32_e32 v5, 2, v5
	global_load_dwordx4 v[50:53], v5, s[64:65]
	global_load_dwordx4 v[54:57], v5, s[64:65] offset:16
	s_lshl_b32 s3, s1, 2
	s_add_u32 s70, s70, s3
	s_addc_u32 s71, s71, 0
	v_lshlrev_b32_e32 v6, 2, v0
	global_load_dword v58, v6, s[70:71]
	s_mul_i32 s3, s2, s9
	s_add_u32 s3, s3, s1
	s_lshl_b32 s3, s3, 1
	s_add_u32 s46, s66, s3
	s_addc_u32 s47, s67, 0
	s_mov_b32 s48, s9
	s_sub_u32 s49, s5, s2
	s_mov_b32 s50, s20
	s_add_u32 s35, s33, 512
	s_cmp_lt_u32 s35, 1152
	s_cbranch_scc0 .Lcv_a_p2_m1
	s_mov_b64 s[64:65], s[18:19]
	s_mov_b32 s5, 1024
	s_mov_b32 s6, 0x10000000
	s_mov_b32 s7, 16
	s_movk_i32 s8, 896
	s_add_u32 s66, s10, 0x700000
	s_addc_u32 s67, s11, 0
	s_movk_i32 s9, 1024
	s_mov_b32 s20, 0
	s_mov_b64 s[70:71], s[24:25]
	s_branch .Lcv_a_p2_c

.Lcv_a_p2_c:
	s_sub_u32 s0, s35, s8
	s_mul_hi_u32 s1, s0, s6
	s_mul_i32 s2, s1, s7
	s_sub_u32 s2, s0, s2
	s_lshl_b32 s1, s1, 6
	s_lshl_b32 s2, s2, 6
	s_mul_i32 s3, s1, s5
	s_lshl_b32 s3, s3, 2
	s_add_u32 s64, s64, s3
	s_addc_u32 s65, s65, 0
	v_add_u32_e32 v5, s2, v1
	s_sub_u32 s4, s5, 8
	v_min_u32_e32 v5, s4, v5
	v_mad_u32_u24 v5, v0, s5, v5
	v_lshlrev_b32_e32 v5, 2, v5
	global_load_dwordx4 v[60:63], v5, s[64:65]
	global_load_dwordx4 v[64:67], v5, s[64:65] offset:16
	s_lshl_b32 s3, s1, 2
	s_add_u32 s70, s70, s3
	s_addc_u32 s71, s71, 0
	v_lshlrev_b32_e32 v6, 2, v0
	global_load_dword v68, v6, s[70:71]
	s_mul_i32 s3, s2, s9
	s_add_u32 s3, s3, s1
	s_lshl_b32 s3, s3, 1
	s_add_u32 s52, s66, s3
	s_addc_u32 s53, s67, 0
	s_mov_b32 s54, s9
	s_sub_u32 s55, s5, s2
	s_mov_b32 s56, s20
	s_add_u32 s35, s33, 768
	s_cmp_lt_u32 s35, 1152
	s_cbranch_scc0 .Lcv_a_p3_m1
	s_mov_b64 s[64:65], s[18:19]
	s_mov_b32 s5, 1024
	s_mov_b32 s6, 0x10000000
	s_mov_b32 s7, 16
	s_movk_i32 s8, 896
	s_add_u32 s66, s10, 0x700000
	s_addc_u32 s67, s11, 0
	s_movk_i32 s9, 1024
	s_mov_b32 s20, 0
	s_mov_b64 s[70:71], s[24:25]
	s_branch .Lcv_a_p3_c

.Lcv_a_p3_c:
	s_sub_u32 s0, s35, s8
	s_mul_hi_u32 s1, s0, s6
	s_mul_i32 s2, s1, s7
	s_sub_u32 s2, s0, s2
	s_lshl_b32 s1, s1, 6
	s_lshl_b32 s2, s2, 6
	s_mul_i32 s3, s1, s5
	s_lshl_b32 s3, s3, 2
	s_add_u32 s64, s64, s3
	s_addc_u32 s65, s65, 0
	v_add_u32_e32 v5, s2, v1
	s_sub_u32 s4, s5, 8
	v_min_u32_e32 v5, s4, v5
	v_mad_u32_u24 v5, v0, s5, v5
	v_lshlrev_b32_e32 v5, 2, v5
	global_load_dwordx4 v[70:73], v5, s[64:65]
	global_load_dwordx4 v[74:77], v5, s[64:65] offset:16
	s_lshl_b32 s3, s1, 2
	s_add_u32 s70, s70, s3
	s_addc_u32 s71, s71, 0
	v_lshlrev_b32_e32 v6, 2, v0
	global_load_dword v78, v6, s[70:71]
	s_mul_i32 s3, s2, s9
	s_add_u32 s3, s3, s1
	s_lshl_b32 s3, s3, 1
	s_add_u32 s58, s66, s3
	s_addc_u32 s59, s67, 0
	s_mov_b32 s60, s9
	s_sub_u32 s61, s5, s2
	s_mov_b32 s62, s20
	s_waitcnt vmcnt(0)
.Lcv_a_loop:
	s_add_u32 s35, s33, 0
	s_cmp_ge_u32 s35, 4032
	s_cbranch_scc1 .Lcv_a_exit
	s_add_u32 s34, s35, 1024
	s_cmp_lt_u32 s34, 4032
	s_cselect_b32 s34, s34, s39
	s_waitcnt vmcnt(13)
	v_cmp_gt_i32_e32 vcc, s43, v1
	s_cmp_eq_u32 s44, 0
	s_cbranch_scc0 .Lcv_a_l0_hs
	v_mov_b32_e32 v48, 1.0
.Lcv_a_l0_hs:
	s_nop 1
	v_mul_f32_e32 v22, v40, v48
	v_cndmask_b32_e32 v22, 0, v22, vcc
	v_mul_f32_e32 v23, v41, v48
	v_cndmask_b32_e32 v23, 0, v23, vcc
	v_mul_f32_e32 v24, v42, v48
	v_cndmask_b32_e32 v24, 0, v24, vcc
	v_mul_f32_e32 v25, v43, v48
	v_cndmask_b32_e32 v25, 0, v25, vcc
	v_mul_f32_e32 v26, v44, v48
	v_cndmask_b32_e32 v26, 0, v26, vcc
	v_mul_f32_e32 v27, v45, v48
	v_cndmask_b32_e32 v27, 0, v27, vcc
	v_mul_f32_e32 v28, v46, v48
	v_cndmask_b32_e32 v28, 0, v28, vcc
	v_mul_f32_e32 v29, v47, v48
	v_cndmask_b32_e32 v29, 0, v29, vcc
	ds_write_b32 v2, v22 offset:0
	ds_write_b32 v2, v23 offset:4
	ds_write_b32 v2, v24 offset:8
	ds_write_b32 v2, v25 offset:12
	ds_write_b32 v2, v26 offset:16
	ds_write_b32 v2, v27 offset:20
	ds_write_b32 v2, v28 offset:24
	ds_write_b32 v2, v29 offset:28
	s_mov_b64 s[36:37], s[40:41]
	s_mov_b32 s38, s42
	s_cmp_lt_u32 s34, 1152
	s_cbranch_scc0 .Lcv_a_l0n_m1
	s_mov_b64 s[64:65], s[18:19]
	s_mov_b32 s5, 1024
	s_mov_b32 s6, 0x10000000
	s_mov_b32 s7, 16
	s_movk_i32 s8, 896
	s_add_u32 s66, s10, 0x700000
	s_addc_u32 s67, s11, 0
	s_movk_i32 s9, 1024
	s_mov_b32 s20, 0
	s_mov_b64 s[70:71], s[24:25]
	s_branch .Lcv_a_l0n_c
.Lcv_a_l0n_m1:
	s_cmp_lt_u32 s34, 2176
	s_cbranch_scc0 .Lcv_a_l0n_m2
	s_mov_b64 s[64:65], s[12:13]
	s_mov_b32 s5, 4096
	s_mov_b32 s6, 0x4000000
	s_mov_b32 s7, 64
	s_movk_i32 s8, 1152
	s_add_u32 s66, s10, 0x900000
	s_addc_u32 s67, s11, 0
	s_movk_i32 s9, 1024
	s_mov_b32 s20, 1
	s_add_u32 s70, s26, 0
	s_addc_u32 s71, s27, 0
	s_branch .Lcv_a_l0n_c
.Lcv_a_l0n_m2:
	s_cmp_lt_u32 s34, 3200
	s_cbranch_scc0 .Lcv_a_l0n_m3
	s_mov_b64 s[64:65], s[14:15]
	s_mov_b32 s5, 1024
	s_mov_b32 s6, 0x10000000
	s_mov_b32 s7, 16
	s_movk_i32 s8, 2176
	s_add_u32 s66, s10, 0x1100000
	s_addc_u32 s67, s11, 0
	s_movk_i32 s9, 4096
	s_mov_b32 s20, 0
	s_mov_b64 s[70:71], s[24:25]
	s_branch .Lcv_a_l0n_c

.Lcv_a_l0n_c:
	s_sub_u32 s0, s34, s8
	s_mul_hi_u32 s1, s0, s6
	s_mul_i32 s2, s1, s7
	s_sub_u32 s2, s0, s2
	s_lshl_b32 s1, s1, 6
	s_lshl_b32 s2, s2, 6
	s_mul_i32 s3, s1, s5
	s_lshl_b32 s3, s3, 2
	s_add_u32 s64, s64, s3
	s_addc_u32 s65, s65, 0
	v_add_u32_e32 v5, s2, v1
	s_sub_u32 s4, s5, 8
	v_min_u32_e32 v5, s4, v5
	v_mad_u32_u24 v5, v0, s5, v5
	v_lshlrev_b32_e32 v5, 2, v5
	global_load_dwordx4 v[40:43], v5, s[64:65]
	global_load_dwordx4 v[44:47], v5, s[64:65] offset:16
	s_lshl_b32 s3, s1, 2
	s_add_u32 s70, s70, s3
	s_addc_u32 s71, s71, 0
	v_lshlrev_b32_e32 v6, 2, v0
	global_load_dword v48, v6, s[70:71]
	s_mul_i32 s3, s2, s9
	s_add_u32 s3, s3, s1
	s_lshl_b32 s3, s3, 1
	s_add_u32 s40, s66, s3
	s_addc_u32 s41, s67, 0
	s_mov_b32 s42, s9
	s_sub_u32 s43, s5, s2
	s_mov_b32 s44, s20
	s_waitcnt lgkmcnt(0)
	s_barrier
	ds_read_b32 v10, v4 offset:0
	ds_read_b32 v11, v4 offset:260
	ds_read_b32 v12, v4 offset:520
	ds_read_b32 v13, v4 offset:780
	ds_read_b32 v14, v4 offset:1040
	ds_read_b32 v15, v4 offset:1300
	ds_read_b32 v16, v4 offset:1560
	ds_read_b32 v17, v4 offset:1820
	v_mad_u32_u24 v7, v0, s38, v1
	v_lshlrev_b32_e32 v7, 1, v7
	s_waitcnt lgkmcnt(0)
	v_cvt_pk_bf16_f32 v18, v10, v11
	v_cvt_pk_bf16_f32 v19, v12, v13
	v_cvt_pk_bf16_f32 v20, v14, v15
	v_cvt_pk_bf16_f32 v21, v16, v17
	global_store_dwordx4 v7, v[18:21], s[36:37]
	s_add_u32 s35, s33, 256
	s_cmp_ge_u32 s35, 4032
	s_cbranch_scc1 .Lcv_a_exit
	s_add_u32 s34, s35, 1024
	s_cmp_lt_u32 s34, 4032
	s_cselect_b32 s34, s34, s39
	s_waitcnt vmcnt(13)
	v_cmp_gt_i32_e32 vcc, s49, v1
	s_cmp_eq_u32 s50, 0
	s_cbranch_scc0 .Lcv_a_l1_hs
	v_mov_b32_e32 v58, 1.0
.Lcv_a_l1_hs:
	s_nop 1
	v_mul_f32_e32 v22, v50, v58
	v_cndmask_b32_e32 v22, 0, v22, vcc
	v_mul_f32_e32 v23, v51, v58
	v_cndmask_b32_e32 v23, 0, v23, vcc
	v_mul_f32_e32 v24, v52, v58
	v_cndmask_b32_e32 v24, 0, v24, vcc
	v_mul_f32_e32 v25, v53, v58
	v_cndmask_b32_e32 v25, 0, v25, vcc
	v_mul_f32_e32 v26, v54, v58
	v_cndmask_b32_e32 v26, 0, v26, vcc
	v_mul_f32_e32 v27, v55, v58
	v_cndmask_b32_e32 v27, 0, v27, vcc
	v_mul_f32_e32 v28, v56, v58
	v_cndmask_b32_e32 v28, 0, v28, vcc
	v_mul_f32_e32 v29, v57, v58
	v_cndmask_b32_e32 v29, 0, v29, vcc
	ds_write_b32 v2, v22 offset:16640
	ds_write_b32 v2, v23 offset:16644
	ds_write_b32 v2, v24 offset:16648
	ds_write_b32 v2, v25 offset:16652
	ds_write_b32 v2, v26 offset:16656
	ds_write_b32 v2, v27 offset:16660
	ds_write_b32 v2, v28 offset:16664
	ds_write_b32 v2, v29 offset:16668
	s_mov_b64 s[36:37], s[46:47]
	s_mov_b32 s38, s48
	s_cmp_lt_u32 s34, 1152
	s_cbranch_scc0 .Lcv_a_l1n_m1
	s_mov_b64 s[64:65], s[18:19]
	s_mov_b32 s5, 1024
	s_mov_b32 s6, 0x10000000
	s_mov_b32 s7, 16
	s_movk_i32 s8, 896
	s_add_u32 s66, s10, 0x700000
	s_addc_u32 s67, s11, 0
	s_movk_i32 s9, 1024
	s_mov_b32 s20, 0
	s_mov_b64 s[70:71], s[24:25]
	s_branch .Lcv_a_l1n_c

.Lcv_a_l1n_c:
	s_sub_u32 s0, s34, s8
	s_mul_hi_u32 s1, s0, s6
	s_mul_i32 s2, s1, s7
	s_sub_u32 s2, s0, s2
	s_lshl_b32 s1, s1, 6
	s_lshl_b32 s2, s2, 6
	s_mul_i32 s3, s1, s5
	s_lshl_b32 s3, s3, 2
	s_add_u32 s64, s64, s3
	s_addc_u32 s65, s65, 0
	v_add_u32_e32 v5, s2, v1
	s_sub_u32 s4, s5, 8
	v_min_u32_e32 v5, s4, v5
	v_mad_u32_u24 v5, v0, s5, v5
	v_lshlrev_b32_e32 v5, 2, v5
	global_load_dwordx4 v[50:53], v5, s[64:65]
	global_load_dwordx4 v[54:57], v5, s[64:65] offset:16
	s_lshl_b32 s3, s1, 2
	s_add_u32 s70, s70, s3
	s_addc_u32 s71, s71, 0
	v_lshlrev_b32_e32 v6, 2, v0
	global_load_dword v58, v6, s[70:71]
	s_mul_i32 s3, s2, s9
	s_add_u32 s3, s3, s1
	s_lshl_b32 s3, s3, 1
	s_add_u32 s46, s66, s3
	s_addc_u32 s47, s67, 0
	s_mov_b32 s48, s9
	s_sub_u32 s49, s5, s2
	s_mov_b32 s50, s20
	s_waitcnt lgkmcnt(0)
	s_barrier
	ds_read_b32 v10, v4 offset:16640
	ds_read_b32 v11, v4 offset:16900
	ds_read_b32 v12, v4 offset:17160
	ds_read_b32 v13, v4 offset:17420
	ds_read_b32 v14, v4 offset:17680
	ds_read_b32 v15, v4 offset:17940
	ds_read_b32 v16, v4 offset:18200
	ds_read_b32 v17, v4 offset:18460
	v_mad_u32_u24 v7, v0, s38, v1
	v_lshlrev_b32_e32 v7, 1, v7
	s_waitcnt lgkmcnt(0)
	v_cvt_pk_bf16_f32 v18, v10, v11
	v_cvt_pk_bf16_f32 v19, v12, v13
	v_cvt_pk_bf16_f32 v20, v14, v15
	v_cvt_pk_bf16_f32 v21, v16, v17
	global_store_dwordx4 v7, v[18:21], s[36:37]
	s_add_u32 s35, s33, 512
	s_cmp_ge_u32 s35, 4032
	s_cbranch_scc1 .Lcv_a_exit
	s_add_u32 s34, s35, 1024
	s_cmp_lt_u32 s34, 4032
	s_cselect_b32 s34, s34, s39
	s_waitcnt vmcnt(13)
	v_cmp_gt_i32_e32 vcc, s55, v1
	s_cmp_eq_u32 s56, 0
	s_cbranch_scc0 .Lcv_a_l2_hs
	v_mov_b32_e32 v68, 1.0
.Lcv_a_l2_hs:
	s_nop 1
	v_mul_f32_e32 v22, v60, v68
	v_cndmask_b32_e32 v22, 0, v22, vcc
	v_mul_f32_e32 v23, v61, v68
	v_cndmask_b32_e32 v23, 0, v23, vcc
	v_mul_f32_e32 v24, v62, v68
	v_cndmask_b32_e32 v24, 0, v24, vcc
	v_mul_f32_e32 v25, v63, v68
	v_cndmask_b32_e32 v25, 0, v25, vcc
	v_mul_f32_e32 v26, v64, v68
	v_cndmask_b32_e32 v26, 0, v26, vcc
	v_mul_f32_e32 v27, v65, v68
	v_cndmask_b32_e32 v27, 0, v27, vcc
	v_mul_f32_e32 v28, v66, v68
	v_cndmask_b32_e32 v28, 0, v28, vcc
	v_mul_f32_e32 v29, v67, v68
	v_cndmask_b32_e32 v29, 0, v29, vcc
	ds_write_b32 v2, v22 offset:0
	ds_write_b32 v2, v23 offset:4
	ds_write_b32 v2, v24 offset:8
	ds_write_b32 v2, v25 offset:12
	ds_write_b32 v2, v26 offset:16
	ds_write_b32 v2, v27 offset:20
	ds_write_b32 v2, v28 offset:24
	ds_write_b32 v2, v29 offset:28
	s_mov_b64 s[36:37], s[52:53]
	s_mov_b32 s38, s54
	s_cmp_lt_u32 s34, 1152
	s_cbranch_scc0 .Lcv_a_l2n_m1
	s_mov_b64 s[64:65], s[18:19]
	s_mov_b32 s5, 1024
	s_mov_b32 s6, 0x10000000
	s_mov_b32 s7, 16
	s_movk_i32 s8, 896
	s_add_u32 s66, s10, 0x700000
	s_addc_u32 s67, s11, 0
	s_movk_i32 s9, 1024
	s_mov_b32 s20, 0
	s_mov_b64 s[70:71], s[24:25]
	s_branch .Lcv_a_l2n_c

.Lcv_a_l2n_c:
	s_sub_u32 s0, s34, s8
	s_mul_hi_u32 s1, s0, s6
	s_mul_i32 s2, s1, s7
	s_sub_u32 s2, s0, s2
	s_lshl_b32 s1, s1, 6
	s_lshl_b32 s2, s2, 6
	s_mul_i32 s3, s1, s5
	s_lshl_b32 s3, s3, 2
	s_add_u32 s64, s64, s3
	s_addc_u32 s65, s65, 0
	v_add_u32_e32 v5, s2, v1
	s_sub_u32 s4, s5, 8
	v_min_u32_e32 v5, s4, v5
	v_mad_u32_u24 v5, v0, s5, v5
	v_lshlrev_b32_e32 v5, 2, v5
	global_load_dwordx4 v[60:63], v5, s[64:65]
	global_load_dwordx4 v[64:67], v5, s[64:65] offset:16
	s_lshl_b32 s3, s1, 2
	s_add_u32 s70, s70, s3
	s_addc_u32 s71, s71, 0
	v_lshlrev_b32_e32 v6, 2, v0
	global_load_dword v68, v6, s[70:71]
	s_mul_i32 s3, s2, s9
	s_add_u32 s3, s3, s1
	s_lshl_b32 s3, s3, 1
	s_add_u32 s52, s66, s3
	s_addc_u32 s53, s67, 0
	s_mov_b32 s54, s9
	s_sub_u32 s55, s5, s2
	s_mov_b32 s56, s20
	s_waitcnt lgkmcnt(0)
	s_barrier
	ds_read_b32 v10, v4 offset:0
	ds_read_b32 v11, v4 offset:260
	ds_read_b32 v12, v4 offset:520
	ds_read_b32 v13, v4 offset:780
	ds_read_b32 v14, v4 offset:1040
	ds_read_b32 v15, v4 offset:1300
	ds_read_b32 v16, v4 offset:1560
	ds_read_b32 v17, v4 offset:1820
	v_mad_u32_u24 v7, v0, s38, v1
	v_lshlrev_b32_e32 v7, 1, v7
	s_waitcnt lgkmcnt(0)
	v_cvt_pk_bf16_f32 v18, v10, v11
	v_cvt_pk_bf16_f32 v19, v12, v13
	v_cvt_pk_bf16_f32 v20, v14, v15
	v_cvt_pk_bf16_f32 v21, v16, v17
	global_store_dwordx4 v7, v[18:21], s[36:37]
	s_add_u32 s35, s33, 768
	s_cmp_ge_u32 s35, 4032
	s_cbranch_scc1 .Lcv_a_exit
	s_add_u32 s34, s35, 1024
	s_cmp_lt_u32 s34, 4032
	s_cselect_b32 s34, s34, s39
	s_waitcnt vmcnt(13)
	v_cmp_gt_i32_e32 vcc, s61, v1
	s_cmp_eq_u32 s62, 0
	s_cbranch_scc0 .Lcv_a_l3_hs
	v_mov_b32_e32 v78, 1.0
.Lcv_a_l3_hs:
	s_nop 1
	v_mul_f32_e32 v22, v70, v78
	v_cndmask_b32_e32 v22, 0, v22, vcc
	v_mul_f32_e32 v23, v71, v78
	v_cndmask_b32_e32 v23, 0, v23, vcc
	v_mul_f32_e32 v24, v72, v78
	v_cndmask_b32_e32 v24, 0, v24, vcc
	v_mul_f32_e32 v25, v73, v78
	v_cndmask_b32_e32 v25, 0, v25, vcc
	v_mul_f32_e32 v26, v74, v78
	v_cndmask_b32_e32 v26, 0, v26, vcc
	v_mul_f32_e32 v27, v75, v78
	v_cndmask_b32_e32 v27, 0, v27, vcc
	v_mul_f32_e32 v28, v76, v78
	v_cndmask_b32_e32 v28, 0, v28, vcc
	v_mul_f32_e32 v29, v77, v78
	v_cndmask_b32_e32 v29, 0, v29, vcc
	ds_write_b32 v2, v22 offset:16640
	ds_write_b32 v2, v23 offset:16644
	ds_write_b32 v2, v24 offset:16648
	ds_write_b32 v2, v25 offset:16652
	ds_write_b32 v2, v26 offset:16656
	ds_write_b32 v2, v27 offset:16660
	ds_write_b32 v2, v28 offset:16664
	ds_write_b32 v2, v29 offset:16668
	s_mov_b64 s[36:37], s[58:59]
	s_mov_b32 s38, s60
	s_cmp_lt_u32 s34, 1152
	s_cbranch_scc0 .Lcv_a_l3n_m1
	s_mov_b64 s[64:65], s[18:19]
	s_mov_b32 s5, 1024
	s_mov_b32 s6, 0x10000000
	s_mov_b32 s7, 16
	s_movk_i32 s8, 896
	s_add_u32 s66, s10, 0x700000
	s_addc_u32 s67, s11, 0
	s_movk_i32 s9, 1024
	s_mov_b32 s20, 0
	s_mov_b64 s[70:71], s[24:25]
	s_branch .Lcv_a_l3n_c

.Lcv_a_l3n_c:
	s_sub_u32 s0, s34, s8
	s_mul_hi_u32 s1, s0, s6
	s_mul_i32 s2, s1, s7
	s_sub_u32 s2, s0, s2
	s_lshl_b32 s1, s1, 6
	s_lshl_b32 s2, s2, 6
	s_mul_i32 s3, s1, s5
	s_lshl_b32 s3, s3, 2
	s_add_u32 s64, s64, s3
	s_addc_u32 s65, s65, 0
	v_add_u32_e32 v5, s2, v1
	s_sub_u32 s4, s5, 8
	v_min_u32_e32 v5, s4, v5
	v_mad_u32_u24 v5, v0, s5, v5
	v_lshlrev_b32_e32 v5, 2, v5
	global_load_dwordx4 v[70:73], v5, s[64:65]
	global_load_dwordx4 v[74:77], v5, s[64:65] offset:16
	s_lshl_b32 s3, s1, 2
	s_add_u32 s70, s70, s3
	s_addc_u32 s71, s71, 0
	v_lshlrev_b32_e32 v6, 2, v0
	global_load_dword v78, v6, s[70:71]
	s_mul_i32 s3, s2, s9
	s_add_u32 s3, s3, s1
	s_lshl_b32 s3, s3, 1
	s_add_u32 s58, s66, s3
	s_addc_u32 s59, s67, 0
	s_mov_b32 s60, s9
	s_sub_u32 s61, s5, s2
	s_mov_b32 s62, s20
	s_waitcnt lgkmcnt(0)
	s_barrier
	ds_read_b32 v10, v4 offset:16640
	ds_read_b32 v11, v4 offset:16900
	ds_read_b32 v12, v4 offset:17160
	ds_read_b32 v13, v4 offset:17420
	ds_read_b32 v14, v4 offset:17680
	ds_read_b32 v15, v4 offset:17940
	ds_read_b32 v16, v4 offset:18200
	ds_read_b32 v17, v4 offset:18460
	v_mad_u32_u24 v7, v0, s38, v1
	v_lshlrev_b32_e32 v7, 1, v7
	s_waitcnt lgkmcnt(0)
	v_cvt_pk_bf16_f32 v18, v10, v11
	v_cvt_pk_bf16_f32 v19, v12, v13
	v_cvt_pk_bf16_f32 v20, v14, v15
	v_cvt_pk_bf16_f32 v21, v16, v17
	global_store_dwordx4 v7, v[18:21], s[36:37]
	s_add_u32 s33, s33, 1024
	s_branch .Lcv_a_loop
.Lcv_a_exit:
	s_waitcnt vmcnt(0)
	s_barrier
	s_branch .LBB0_152
	s_cmp_lt_i32 s97, s22
	s_cselect_b64 s[0:1], -1, 0
	s_and_b64 s[0:1], s[76:77], s[0:1]
	v_mov_b32_e32 v0, v204
	s_andn2_b64 vcc, exec, s[0:1]
	s_cbranch_vccnz .LBB0_152
	s_add_i32 s0, s97, 0x380
	s_cmpk_lt_u32 s97, 0xc40
	s_cselect_b64 s[8:9], -1, 0
	s_and_b64 s[2:3], s[8:9], exec
	s_cselect_b32 s1, s0, 0x380
	s_cmpk_gt_u32 s1, 0x47f
	s_cbranch_scc0 .LBB0_123
	s_cmpk_gt_u32 s1, 0x87f
	s_cbranch_scc0 .LBB0_124
	s_cmpk_gt_u32 s1, 0xc7f
	s_cbranch_scc0 .Lisl_1158
	s_waitcnt lgkmcnt(0)
	s_add_u32 s4, s10, 0x1900000
	s_addc_u32 s5, s11, 0
	s_add_u32 s38, s24, 0x1000
	s_addc_u32 s39, s25, 0
	s_mov_b64 s[40:41], s[28:29]
	s_cbranch_execz .Lisl_1159
	s_mov_b32 s3, 52
	s_movk_i32 s20, 0xf380
	s_mov_b64 s[6:7], 0x400
	s_movk_i32 s2, 0xc20
	s_cbranch_execz .LBB0_125
	s_branch .LBB0_126

.LBB0_164:
	s_andn2_b64 vcc, exec, s[30:31]
	s_cbranch_vccnz .LBB0_200
	s_waitcnt lgkmcnt(0)
	v_lshrrev_b32_e32 v0, 3, v204
	v_and_b32_e32 v1, 7, v204
	v_lshlrev_b32_e32 v1, 3, v1
	v_mul_u32_u24_e32 v2, 65, v0
	v_add_lshl_u32 v2, v2, v1, 2
	v_mul_u32_u24_e32 v4, 65, v1
	v_add_lshl_u32 v4, v4, v0, 2
	s_add_u32 s39, s97, 896
	s_mov_b32 s33, s39
	s_add_u32 s35, s33, 0
	s_cmp_lt_u32 s35, 1152
	s_cbranch_scc0 .Lcv_b_p0_m1
	s_mov_b64 s[64:65], s[18:19]
	s_mov_b32 s5, 1024
	s_mov_b32 s6, 0x10000000
	s_mov_b32 s7, 16
	s_movk_i32 s8, 896
	s_add_u32 s66, s10, 0x700000
	s_addc_u32 s67, s11, 0
	s_movk_i32 s9, 1024
	s_mov_b32 s20, 0
	s_mov_b64 s[70:71], s[24:25]
	s_branch .Lcv_b_p0_c

.Lcv_b_exit:
	s_waitcnt vmcnt(0)
	s_barrier
	s_branch .LBB0_200
	s_cmp_lt_i32 s97, s22
	s_cselect_b64 s[0:1], -1, 0
	s_and_b64 s[0:1], s[76:77], s[0:1]
	v_mov_b32_e32 v0, v204
	s_andn2_b64 vcc, exec, s[0:1]
	s_cbranch_vccnz .LBB0_200
	s_add_i32 s0, s97, 0x380
	s_cmpk_lt_u32 s97, 0xc40
	s_cselect_b64 s[8:9], -1, 0
	s_and_b64 s[2:3], s[8:9], exec
	s_cselect_b32 s1, s0, 0x380
	s_cmpk_gt_u32 s1, 0x47f
	s_cbranch_scc0 .LBB0_171
	s_cmpk_gt_u32 s1, 0x87f
	s_cbranch_scc0 .LBB0_172
	s_cmpk_gt_u32 s1, 0xc7f
	s_cbranch_scc0 .Lisl_1160
	s_waitcnt lgkmcnt(0)
	s_add_u32 s4, s10, 0x1900000
	s_addc_u32 s5, s11, 0
	s_add_u32 s36, s24, 0x1000
	s_addc_u32 s37, s25, 0
	s_mov_b64 s[38:39], s[28:29]
	s_cbranch_execz .Lisl_1161
	s_mov_b32 s3, 52
	s_movk_i32 s20, 0xf380
	s_mov_b64 s[6:7], 0x400
	s_movk_i32 s2, 0xc20
	s_cbranch_execz .LBB0_173
	s_branch .LBB0_174
